# gate epilogue: the hoisted u-row loads also widened (16 dwordx2 -> 8 dwordx4 per group) and redistributed with v_permlane16_swap
# speedup vs baseline: 1.0100x; 1.0023x over previous
.LBB0_792:
	s_or_b64 exec, exec, s[38:39]
	v_lshl_add_u64 v[110:111], s[42:43], 0, v[70:71]
	v_add_co_u32_e32 v0, vcc, 0x3600000, v110
	ds_write_b128 v130, v[24:27] offset:60928
	s_nop 0
	v_addc_co_u32_e32 v1, vcc, 0, v111, vcc
	v_add_co_u32_e32 v4, vcc, 0x3601000, v110
	s_waitcnt lgkmcnt(0)
	s_nop 0
	v_addc_co_u32_e32 v5, vcc, 0, v111, vcc
	s_barrier
	v_bfe_u32 v174, v194, 4, 1
	v_mul_u32_u24_e32 v174, 24, v174
	v_mov_b32_e32 v175, 0
	s_and_saveexec_b64 s[100:101], s[22:23]
	global_load_dword v200, v[66:67], off offset:-64
	v_lshl_add_u64 v[248:249], s[42:43], 0, v[94:95]
	v_lshl_add_u64 v[248:249], v[248:249], 0, v[174:175]
	global_load_dwordx4 v[202:205], v[248:249], off offset:-128
	global_load_dwordx4 v[206:209], v[248:249], off offset:-64
	global_load_dwordx4 v[210:213], v[248:249], off
	global_load_dwordx4 v[214:217], v[248:249], off offset:64
	s_or_b64 exec, exec, s[100:101]
	s_and_saveexec_b64 s[100:101], s[24:25]
	global_load_dword v201, v[66:67], off
	v_lshl_add_u64 v[250:251], s[42:43], 0, v[108:109]
	v_lshl_add_u64 v[250:251], v[250:251], 0, v[174:175]
	global_load_dwordx4 v[218:221], v[250:251], off offset:-128
	global_load_dwordx4 v[222:225], v[250:251], off offset:-64
	global_load_dwordx4 v[226:229], v[250:251], off
	global_load_dwordx4 v[230:233], v[250:251], off offset:64
	s_or_b64 exec, exec, s[100:101]
	global_load_dwordx4 v[0:3], v[0:1], off
	s_andn2_b64 vcc, exec, s[54:55]
	global_load_dwordx4 v[132:135], v[4:5], off
	ds_read_b64_tr_b16 v[4:5], v122
	ds_read_b64_tr_b16 v[6:7], v122 offset:2176
	ds_read_b64_tr_b16 v[10:11], v122 offset:2208
	ds_read_b64_tr_b16 v[8:9], v122 offset:32
	ds_read_b64_tr_b16 v[12:13], v122 offset:64
	ds_read_b64_tr_b16 v[16:17], v122 offset:96
	ds_read_b64_tr_b16 v[14:15], v122 offset:2240
	ds_read_b64_tr_b16 v[18:19], v122 offset:2272
	ds_read_b64_tr_b16 v[136:137], v122 offset:128
	ds_read_b64_tr_b16 v[138:139], v122 offset:2304
	ds_read_b64_tr_b16 v[142:143], v122 offset:2336
	ds_read_b64_tr_b16 v[140:141], v122 offset:160
	ds_read_b64_tr_b16 v[144:145], v122 offset:192
	ds_read_b64_tr_b16 v[148:149], v122 offset:224
	ds_read_b64_tr_b16 v[146:147], v122 offset:2368
	ds_read_b64_tr_b16 v[150:151], v122 offset:2400
	s_waitcnt vmcnt(1) lgkmcnt(14)
	v_mfma_f32_16x16x32_bf16 v[40:43], v[4:7], v[0:3], 0
	s_waitcnt lgkmcnt(12)
	v_mfma_f32_16x16x32_bf16 v[36:39], v[8:11], v[0:3], 0
	s_waitcnt lgkmcnt(9)
	v_mfma_f32_16x16x32_bf16 v[44:47], v[12:15], v[0:3], 0
	s_waitcnt lgkmcnt(8)
	v_mfma_f32_16x16x32_bf16 v[48:51], v[16:19], v[0:3], 0
	s_waitcnt lgkmcnt(6)
	v_mfma_f32_16x16x32_bf16 v[60:63], v[136:139], v[0:3], 0
	s_waitcnt lgkmcnt(4)
	v_mfma_f32_16x16x32_bf16 v[56:59], v[140:143], v[0:3], 0
	s_waitcnt lgkmcnt(1)
	v_mfma_f32_16x16x32_bf16 v[52:55], v[144:147], v[0:3], 0
	s_waitcnt lgkmcnt(0)
	v_mfma_f32_16x16x32_bf16 v[32:35], v[148:151], v[0:3], 0
	s_waitcnt vmcnt(0)
	v_mfma_f32_16x16x32_bf16 v[28:31], v[4:7], v[132:135], 0
	v_mfma_f32_16x16x32_bf16 v[24:27], v[8:11], v[132:135], 0
	v_mfma_f32_16x16x32_bf16 v[20:23], v[12:15], v[132:135], 0
	v_mfma_f32_16x16x32_bf16 v[16:19], v[16:19], v[132:135], 0
	v_mfma_f32_16x16x32_bf16 v[12:15], v[136:139], v[132:135], 0
	v_mfma_f32_16x16x32_bf16 v[8:11], v[140:143], v[132:135], 0
	v_mfma_f32_16x16x32_bf16 v[4:7], v[144:147], v[132:135], 0
	v_mfma_f32_16x16x32_bf16 v[0:3], v[148:151], v[132:135], 0
	s_cbranch_vccnz .LBB0_794
	v_add_co_u32_e32 v132, vcc, 0x3600000, v110
	s_nop 1
	v_addc_co_u32_e32 v133, vcc, 0, v111, vcc
	v_add_co_u32_e32 v136, vcc, 0x3601000, v110
	global_load_dwordx4 v[132:135], v[132:133], off offset:64
	s_nop 0
	v_addc_co_u32_e32 v137, vcc, 0, v111, vcc
	global_load_dwordx4 v[136:139], v[136:137], off offset:64
	ds_read_b64_tr_b16 v[140:141], v122 offset:17408
	ds_read_b64_tr_b16 v[142:143], v122 offset:19584
	ds_read_b64_tr_b16 v[146:147], v122 offset:19616
	ds_read_b64_tr_b16 v[144:145], v122 offset:17440
	ds_read_b64_tr_b16 v[148:149], v122 offset:17472
	ds_read_b64_tr_b16 v[152:153], v122 offset:17504
	ds_read_b64_tr_b16 v[150:151], v122 offset:19648
	ds_read_b64_tr_b16 v[154:155], v122 offset:19680
	ds_read_b64_tr_b16 v[156:157], v122 offset:17536
	ds_read_b64_tr_b16 v[158:159], v122 offset:19712
	ds_read_b64_tr_b16 v[162:163], v122 offset:19744
	ds_read_b64_tr_b16 v[160:161], v122 offset:17568
	ds_read_b64_tr_b16 v[164:165], v122 offset:17600
	ds_read_b64_tr_b16 v[168:169], v122 offset:17632
	ds_read_b64_tr_b16 v[166:167], v122 offset:19776
	ds_read_b64_tr_b16 v[170:171], v122 offset:19808
	s_waitcnt vmcnt(1) lgkmcnt(14)
	v_mfma_f32_16x16x32_bf16 v[40:43], v[140:143], v[132:135], v[40:43]
	s_waitcnt lgkmcnt(12)
	v_mfma_f32_16x16x32_bf16 v[36:39], v[144:147], v[132:135], v[36:39]
	s_waitcnt lgkmcnt(9)
	v_mfma_f32_16x16x32_bf16 v[44:47], v[148:151], v[132:135], v[44:47]
	s_waitcnt lgkmcnt(8)
	v_mfma_f32_16x16x32_bf16 v[48:51], v[152:155], v[132:135], v[48:51]
	s_waitcnt lgkmcnt(6)
	v_mfma_f32_16x16x32_bf16 v[60:63], v[156:159], v[132:135], v[60:63]
	s_waitcnt lgkmcnt(4)
	v_mfma_f32_16x16x32_bf16 v[56:59], v[160:163], v[132:135], v[56:59]
	s_waitcnt lgkmcnt(1)
	v_mfma_f32_16x16x32_bf16 v[52:55], v[164:167], v[132:135], v[52:55]
	s_waitcnt lgkmcnt(0)
	v_mfma_f32_16x16x32_bf16 v[32:35], v[168:171], v[132:135], v[32:35]
	s_waitcnt vmcnt(0)
	v_mfma_f32_16x16x32_bf16 v[28:31], v[140:143], v[136:139], v[28:31]
	v_mfma_f32_16x16x32_bf16 v[24:27], v[144:147], v[136:139], v[24:27]
	v_mfma_f32_16x16x32_bf16 v[20:23], v[148:151], v[136:139], v[20:23]
	v_mfma_f32_16x16x32_bf16 v[16:19], v[152:155], v[136:139], v[16:19]
	v_mfma_f32_16x16x32_bf16 v[12:15], v[156:159], v[136:139], v[12:15]
	v_mfma_f32_16x16x32_bf16 v[8:11], v[160:163], v[136:139], v[8:11]
	v_mfma_f32_16x16x32_bf16 v[4:7], v[164:167], v[136:139], v[4:7]
	v_mfma_f32_16x16x32_bf16 v[0:3], v[168:171], v[136:139], v[0:3]

.LBB0_797:
	s_waitcnt vmcnt(0)
	v_mov_b32_e32 v110, v200
	v_lshl_add_u64 v[132:133], s[42:43], 0, v[94:95]
	v_permlane16_swap_b32 v202, v204
	v_permlane16_swap_b32 v203, v205
	v_permlane16_swap_b32 v206, v208
	v_permlane16_swap_b32 v207, v209
	v_permlane16_swap_b32 v210, v212
	v_permlane16_swap_b32 v211, v213
	v_permlane16_swap_b32 v214, v216
	v_permlane16_swap_b32 v215, v217
	v_mov_b32_e32 v134, v202
	v_mov_b32_e32 v135, v203
	v_mov_b32_e32 v136, v204
	v_mov_b32_e32 v137, v205
	v_mov_b32_e32 v138, v206
	v_mov_b32_e32 v139, v207
	v_mov_b32_e32 v140, v208
	v_mov_b32_e32 v141, v209
	v_mov_b32_e32 v142, v210
	v_mov_b32_e32 v143, v211
	v_mov_b32_e32 v144, v212
	v_mov_b32_e32 v145, v213
	v_mov_b32_e32 v146, v214
	v_mov_b32_e32 v147, v215
	v_mov_b32_e32 v148, v216
	v_mov_b32_e32 v149, v217
	s_waitcnt vmcnt(7)
	v_lshlrev_b32_e32 v150, 16, v134
	v_and_b32_e32 v151, 0xffff0000, v134
	v_lshlrev_b32_e32 v134, 16, v135
	v_and_b32_e32 v135, 0xffff0000, v135
	s_waitcnt vmcnt(6)
	v_lshlrev_b32_e32 v152, 16, v136
	v_pk_add_f32 v[42:43], v[42:43], v[110:111] op_sel_hi:[1,0]
	v_pk_add_f32 v[40:41], v[40:41], v[110:111] op_sel_hi:[1,0]
	v_pk_add_f32 v[38:39], v[38:39], v[110:111] op_sel_hi:[1,0]
	v_pk_add_f32 v[36:37], v[36:37], v[110:111] op_sel_hi:[1,0]
	v_and_b32_e32 v153, 0xffff0000, v136
	v_lshlrev_b32_e32 v136, 16, v137
	v_and_b32_e32 v137, 0xffff0000, v137
	v_pk_add_f32 v[46:47], v[46:47], v[110:111] op_sel_hi:[1,0]
	v_pk_add_f32 v[44:45], v[44:45], v[110:111] op_sel_hi:[1,0]
	v_pk_add_f32 v[50:51], v[50:51], v[110:111] op_sel_hi:[1,0]
	v_pk_add_f32 v[48:49], v[48:49], v[110:111] op_sel_hi:[1,0]
	v_pk_add_f32 v[62:63], v[62:63], v[110:111] op_sel_hi:[1,0]
	v_pk_add_f32 v[60:61], v[60:61], v[110:111] op_sel_hi:[1,0]
	v_pk_add_f32 v[58:59], v[58:59], v[110:111] op_sel_hi:[1,0]
	v_pk_add_f32 v[56:57], v[56:57], v[110:111] op_sel_hi:[1,0]
	s_waitcnt vmcnt(5)
	v_lshlrev_b32_e32 v154, 16, v138
	v_and_b32_e32 v155, 0xffff0000, v138
	v_lshlrev_b32_e32 v138, 16, v139
	v_and_b32_e32 v139, 0xffff0000, v139
	s_waitcnt vmcnt(4)
	v_lshlrev_b32_e32 v156, 16, v140
	v_and_b32_e32 v157, 0xffff0000, v140
	v_lshlrev_b32_e32 v140, 16, v141
	v_and_b32_e32 v141, 0xffff0000, v141
	s_waitcnt vmcnt(3)
	v_lshlrev_b32_e32 v158, 16, v142
	v_and_b32_e32 v159, 0xffff0000, v142
	v_lshlrev_b32_e32 v142, 16, v143
	v_and_b32_e32 v143, 0xffff0000, v143
	s_waitcnt vmcnt(2)
	v_lshlrev_b32_e32 v160, 16, v144
	v_and_b32_e32 v161, 0xffff0000, v144
	v_lshlrev_b32_e32 v144, 16, v145
	v_and_b32_e32 v145, 0xffff0000, v145
	v_pk_mul_f32 v[40:41], v[40:41], v[150:151]
	v_pk_mul_f32 v[42:43], v[42:43], v[134:135]
	v_pk_mul_f32 v[36:37], v[36:37], v[152:153]
	v_pk_mul_f32 v[38:39], v[38:39], v[136:137]
	v_pk_mul_f32 v[44:45], v[44:45], v[154:155]
	v_pk_mul_f32 v[46:47], v[46:47], v[138:139]
	v_pk_mul_f32 v[48:49], v[48:49], v[156:157]
	v_pk_mul_f32 v[50:51], v[50:51], v[140:141]
	v_pk_mul_f32 v[60:61], v[60:61], v[158:159]
	v_pk_mul_f32 v[62:63], v[62:63], v[142:143]
	v_pk_mul_f32 v[56:57], v[56:57], v[160:161]
	v_pk_mul_f32 v[58:59], v[58:59], v[144:145]
	v_cvt_pk_bf16_f32 v40, v40, v41
	v_cvt_pk_bf16_f32 v41, v42, v43
	v_cvt_pk_bf16_f32 v42, v36, v37
	v_cvt_pk_bf16_f32 v43, v38, v39
	v_cvt_pk_bf16_f32 v36, v44, v45
	v_cvt_pk_bf16_f32 v37, v46, v47
	v_cvt_pk_bf16_f32 v38, v48, v49
	v_cvt_pk_bf16_f32 v39, v50, v51
	v_cvt_pk_bf16_f32 v44, v60, v61
	v_cvt_pk_bf16_f32 v45, v62, v63
	v_cvt_pk_bf16_f32 v46, v56, v57
	v_cvt_pk_bf16_f32 v47, v58, v59
	v_bfe_u32 v174, v194, 4, 1
	v_mul_u32_u24_e32 v174, 24, v174
	v_mov_b32_e32 v175, 0
	v_lshl_add_u64 v[176:177], v[132:133], 0, v[174:175]
	s_nop 1
	v_permlane16_swap_b32 v40, v42
	v_permlane16_swap_b32 v41, v43
	v_permlane16_swap_b32 v36, v38
	v_permlane16_swap_b32 v37, v39
	v_permlane16_swap_b32 v44, v46
	v_permlane16_swap_b32 v45, v47
	global_store_dwordx4 v[176:177], v[40:43], off offset:-128
	global_store_dwordx4 v[176:177], v[36:39], off offset:-64
	global_store_dwordx4 v[176:177], v[44:47], off
	v_pk_add_f32 v[32:33], v[32:33], v[110:111] op_sel_hi:[1,0]
	s_waitcnt vmcnt(6)
	v_lshlrev_b32_e32 v36, 16, v148
	v_and_b32_e32 v37, 0xffff0000, v148
	v_pk_add_f32 v[54:55], v[54:55], v[110:111] op_sel_hi:[1,0]
	v_pk_add_f32 v[52:53], v[52:53], v[110:111] op_sel_hi:[1,0]
	v_lshlrev_b32_e32 v162, 16, v146
	v_and_b32_e32 v163, 0xffff0000, v146
	v_lshlrev_b32_e32 v146, 16, v147
	v_and_b32_e32 v147, 0xffff0000, v147
	v_pk_add_f32 v[34:35], v[34:35], v[110:111] op_sel_hi:[1,0]
	v_pk_mul_f32 v[32:33], v[32:33], v[36:37]
	v_lshlrev_b32_e32 v36, 16, v149
	v_and_b32_e32 v37, 0xffff0000, v149
	v_pk_mul_f32 v[52:53], v[52:53], v[162:163]
	v_pk_mul_f32 v[54:55], v[54:55], v[146:147]
	v_pk_mul_f32 v[34:35], v[34:35], v[36:37]
	v_cvt_pk_bf16_f32 v48, v52, v53
	v_cvt_pk_bf16_f32 v49, v54, v55
	v_cvt_pk_bf16_f32 v50, v32, v33
	v_cvt_pk_bf16_f32 v51, v34, v35
	s_nop 1
	v_permlane16_swap_b32 v48, v50
	v_permlane16_swap_b32 v49, v51
	global_store_dwordx4 v[176:177], v[48:51], off offset:64
	s_or_b64 exec, exec, s[26:27]
	s_and_saveexec_b64 s[26:27], s[24:25]
	s_cbranch_execz .LBB0_743
	s_branch .LBB0_801

.LBB0_801:
	v_mov_b32_e32 v32, v201
	v_lshl_add_u64 v[34:35], s[42:43], 0, v[108:109]
	v_permlane16_swap_b32 v218, v220
	v_permlane16_swap_b32 v219, v221
	v_permlane16_swap_b32 v222, v224
	v_permlane16_swap_b32 v223, v225
	v_permlane16_swap_b32 v226, v228
	v_permlane16_swap_b32 v227, v229
	v_permlane16_swap_b32 v230, v232
	v_permlane16_swap_b32 v231, v233
	v_mov_b32_e32 v36, v218
	v_mov_b32_e32 v37, v219
	v_mov_b32_e32 v38, v220
	v_mov_b32_e32 v39, v221
	v_mov_b32_e32 v40, v222
	v_mov_b32_e32 v41, v223
	v_mov_b32_e32 v42, v224
	v_mov_b32_e32 v43, v225
	v_mov_b32_e32 v44, v226
	v_mov_b32_e32 v45, v227
	v_mov_b32_e32 v46, v228
	v_mov_b32_e32 v47, v229
	v_mov_b32_e32 v48, v230
	v_mov_b32_e32 v49, v231
	v_mov_b32_e32 v50, v232
	v_mov_b32_e32 v51, v233
	v_lshlrev_b32_e32 v52, 16, v36
	v_and_b32_e32 v53, 0xffff0000, v36
	v_lshlrev_b32_e32 v36, 16, v37
	v_and_b32_e32 v37, 0xffff0000, v37
	v_lshlrev_b32_e32 v54, 16, v38
	v_pk_add_f32 v[30:31], v[30:31], v[32:33] op_sel_hi:[1,0]
	v_pk_add_f32 v[28:29], v[28:29], v[32:33] op_sel_hi:[1,0]
	v_pk_add_f32 v[6:7], v[6:7], v[32:33] op_sel_hi:[1,0]
	v_pk_add_f32 v[4:5], v[4:5], v[32:33] op_sel_hi:[1,0]
	v_lshlrev_b32_e32 v110, 16, v48
	v_and_b32_e32 v111, 0xffff0000, v48
	v_lshlrev_b32_e32 v48, 16, v49
	v_and_b32_e32 v49, 0xffff0000, v49
	v_pk_add_f32 v[26:27], v[26:27], v[32:33] op_sel_hi:[1,0]
	v_pk_add_f32 v[24:25], v[24:25], v[32:33] op_sel_hi:[1,0]
	v_pk_add_f32 v[22:23], v[22:23], v[32:33] op_sel_hi:[1,0]
	v_pk_add_f32 v[20:21], v[20:21], v[32:33] op_sel_hi:[1,0]
	v_pk_add_f32 v[18:19], v[18:19], v[32:33] op_sel_hi:[1,0]
	v_pk_add_f32 v[16:17], v[16:17], v[32:33] op_sel_hi:[1,0]
	v_pk_add_f32 v[14:15], v[14:15], v[32:33] op_sel_hi:[1,0]
	v_pk_add_f32 v[12:13], v[12:13], v[32:33] op_sel_hi:[1,0]
	v_pk_add_f32 v[10:11], v[10:11], v[32:33] op_sel_hi:[1,0]
	v_pk_add_f32 v[8:9], v[8:9], v[32:33] op_sel_hi:[1,0]
	v_and_b32_e32 v55, 0xffff0000, v38
	v_lshlrev_b32_e32 v38, 16, v39
	v_and_b32_e32 v39, 0xffff0000, v39
	v_lshlrev_b32_e32 v56, 16, v40
	v_and_b32_e32 v57, 0xffff0000, v40
	v_lshlrev_b32_e32 v40, 16, v41
	v_and_b32_e32 v41, 0xffff0000, v41
	v_lshlrev_b32_e32 v58, 16, v42
	v_and_b32_e32 v59, 0xffff0000, v42
	v_lshlrev_b32_e32 v42, 16, v43
	v_and_b32_e32 v43, 0xffff0000, v43
	v_lshlrev_b32_e32 v60, 16, v44
	v_and_b32_e32 v61, 0xffff0000, v44
	v_lshlrev_b32_e32 v44, 16, v45
	v_and_b32_e32 v45, 0xffff0000, v45
	v_lshlrev_b32_e32 v62, 16, v46
	v_and_b32_e32 v63, 0xffff0000, v46
	v_lshlrev_b32_e32 v46, 16, v47
	v_and_b32_e32 v47, 0xffff0000, v47
	v_pk_mul_f32 v[28:29], v[28:29], v[52:53]
	v_pk_mul_f32 v[30:31], v[30:31], v[36:37]
	v_pk_mul_f32 v[4:5], v[4:5], v[110:111]
	v_pk_mul_f32 v[6:7], v[6:7], v[48:49]
	v_pk_mul_f32 v[24:25], v[24:25], v[54:55]
	v_pk_mul_f32 v[26:27], v[26:27], v[38:39]
	v_pk_mul_f32 v[20:21], v[20:21], v[56:57]
	v_pk_mul_f32 v[22:23], v[22:23], v[40:41]
	v_pk_mul_f32 v[16:17], v[16:17], v[58:59]
	v_pk_mul_f32 v[18:19], v[18:19], v[42:43]
	v_pk_mul_f32 v[12:13], v[12:13], v[60:61]
	v_pk_mul_f32 v[14:15], v[14:15], v[44:45]
	v_pk_mul_f32 v[8:9], v[8:9], v[62:63]
	v_pk_mul_f32 v[10:11], v[10:11], v[46:47]
	v_cvt_pk_bf16_f32 v28, v28, v29
	v_cvt_pk_bf16_f32 v29, v30, v31
	v_cvt_pk_bf16_f32 v4, v4, v5
	v_cvt_pk_bf16_f32 v5, v6, v7
	v_cvt_pk_bf16_f32 v30, v24, v25
	v_cvt_pk_bf16_f32 v31, v26, v27
	v_cvt_pk_bf16_f32 v20, v20, v21
	v_cvt_pk_bf16_f32 v21, v22, v23
	v_cvt_pk_bf16_f32 v22, v16, v17
	v_cvt_pk_bf16_f32 v23, v18, v19
	v_cvt_pk_bf16_f32 v12, v12, v13
	v_cvt_pk_bf16_f32 v13, v14, v15
	v_cvt_pk_bf16_f32 v14, v8, v9
	v_cvt_pk_bf16_f32 v15, v10, v11
	v_bfe_u32 v174, v194, 4, 1
	v_mul_u32_u24_e32 v174, 24, v174
	v_mov_b32_e32 v175, 0
	v_lshl_add_u64 v[178:179], v[34:35], 0, v[174:175]
	s_nop 1
	v_permlane16_swap_b32 v28, v30
	v_permlane16_swap_b32 v29, v31
	v_permlane16_swap_b32 v20, v22
	v_permlane16_swap_b32 v21, v23
	v_permlane16_swap_b32 v12, v14
	v_permlane16_swap_b32 v13, v15
	global_store_dwordx4 v[178:179], v[28:31], off offset:-128
	global_store_dwordx4 v[178:179], v[20:23], off offset:-64
	global_store_dwordx4 v[178:179], v[12:15], off
	v_pk_add_f32 v[0:1], v[0:1], v[32:33] op_sel_hi:[1,0]
	v_lshlrev_b32_e32 v172, 16, v50
	v_and_b32_e32 v173, 0xffff0000, v50
	v_pk_add_f32 v[2:3], v[2:3], v[32:33] op_sel_hi:[1,0]
	v_pk_mul_f32 v[0:1], v[0:1], v[172:173]
	v_lshlrev_b32_e32 v172, 16, v51
	v_and_b32_e32 v173, 0xffff0000, v51
	v_pk_mul_f32 v[2:3], v[2:3], v[172:173]
	v_cvt_pk_bf16_f32 v6, v0, v1
	v_cvt_pk_bf16_f32 v7, v2, v3
	s_nop 1
	v_permlane16_swap_b32 v4, v6
	v_permlane16_swap_b32 v5, v7
	global_store_dwordx4 v[178:179], v[4:7], off offset:64
	s_branch .LBB0_743
